# gate/up and down GEMM epilogue stores made write-through (sc1) so the grid barrier L2 writeback has less dirty data
# baseline (speedup 1.0000x reference)
.LBB0_1100:
	v_lshl_add_u32 v150, s3, 10, v148
	ds_read2_b32 v[152:153], v150 offset1:16
	v_lshl_or_b32 v140, s2, 7, v147
	s_lshl_b32 s2, s24, 8
	v_ashrrev_i32_e32 v141, 31, v140
	s_andn2_b64 vcc, exec, s[4:5]
	s_waitcnt lgkmcnt(0)
	v_pk_mul_f32 v[126:127], v[126:127], v[152:153] op_sel_hi:[1,0]
	v_pk_mul_f32 v[122:123], v[122:123], v[152:153] op_sel_hi:[1,0]
	v_mul_f32_e32 v151, 0xbfb8aa3b, v126
	v_exp_f32_e32 v151, v151
	v_pk_mul_f32 v[124:125], v[124:125], v[152:153] op_sel_hi:[1,0]
	v_pk_mul_f32 v[118:119], v[118:119], v[152:153] op_sel_hi:[1,0]
	v_pk_mul_f32 v[114:115], v[114:115], v[152:153] op_sel_hi:[1,0]
	v_add_f32_e32 v151, 1.0, v151
	v_rcp_f32_e32 v154, v151
	v_mul_f32_e32 v151, 0xbfb8aa3b, v127
	v_exp_f32_e32 v151, v151
	v_pk_mul_f32 v[116:117], v[116:117], v[152:153] op_sel_hi:[1,0]
	v_add_f32_e32 v151, 1.0, v151
	v_rcp_f32_e32 v155, v151
	s_nop 0
	v_pk_mul_f32 v[126:127], v[126:127], v[154:155]
	s_nop 0
	v_pk_mul_f32 v[122:123], v[122:123], v[126:127]
	v_pk_mul_f32 v[126:127], v[128:129], v[152:153] op_sel_hi:[1,0]
	s_nop 0
	v_mul_f32_e32 v128, 0xbfb8aa3b, v126
	v_mul_f32_e32 v129, 0xbfb8aa3b, v127
	v_exp_f32_e32 v128, v128
	v_exp_f32_e32 v129, v129
	v_add_f32_e32 v128, 1.0, v128
	v_add_f32_e32 v129, 1.0, v129
	v_rcp_f32_e32 v128, v128
	v_rcp_f32_e32 v129, v129
	s_nop 0
	v_pk_mul_f32 v[126:127], v[126:127], v[128:129]
	s_nop 0
	v_pk_mul_f32 v[124:125], v[124:125], v[126:127]
	v_mul_f32_e32 v126, 0xbfb8aa3b, v118
	v_mul_f32_e32 v127, 0xbfb8aa3b, v119
	v_exp_f32_e32 v126, v126
	v_exp_f32_e32 v127, v127
	v_add_f32_e32 v126, 1.0, v126
	v_add_f32_e32 v127, 1.0, v127
	v_rcp_f32_e32 v126, v126
	v_rcp_f32_e32 v127, v127
	s_nop 0
	v_pk_mul_f32 v[118:119], v[118:119], v[126:127]
	s_nop 0
	v_pk_mul_f32 v[114:115], v[114:115], v[118:119]
	v_pk_mul_f32 v[118:119], v[120:121], v[152:153] op_sel_hi:[1,0]
	s_nop 0
	v_mul_f32_e32 v120, 0xbfb8aa3b, v118
	v_mul_f32_e32 v121, 0xbfb8aa3b, v119
	v_exp_f32_e32 v120, v120
	v_exp_f32_e32 v121, v121
	v_add_f32_e32 v120, 1.0, v120
	v_add_f32_e32 v121, 1.0, v121
	v_rcp_f32_e32 v120, v120
	v_rcp_f32_e32 v121, v121
	s_nop 0
	v_pk_mul_f32 v[118:119], v[118:119], v[120:121]
	s_nop 0
	v_pk_mul_f32 v[116:117], v[116:117], v[118:119]
	v_cvt_pk_bf16_f32 v120, v122, v123
	v_cvt_pk_bf16_f32 v122, v114, v115
	v_add_u32_e32 v118, s2, v142
	v_mov_b64_e32 v[114:115], s[12:13]
	v_cvt_pk_bf16_f32 v121, v124, v125
	v_cvt_pk_bf16_f32 v123, v116, v117
	v_mad_i64_i32 v[124:125], s[24:25], v118, s63, v[114:115]
	v_lshlrev_b64 v[116:117], 1, v[140:141]
	v_lshl_add_u64 v[124:125], v[124:125], 0, v[116:117]
	global_store_dwordx4 v[124:125], v[120:123], off sc1
	s_nop 1
	v_mov_b32_e32 v120, v153
	v_pk_mul_f32 v[110:111], v[110:111], v[120:121] op_sel_hi:[1,0]
	v_pk_mul_f32 v[106:107], v[106:107], v[120:121] op_sel_hi:[1,0]
	v_mul_f32_e32 v119, 0xbfb8aa3b, v110
	v_exp_f32_e32 v119, v119
	v_pk_mul_f32 v[108:109], v[108:109], v[120:121] op_sel_hi:[1,0]
	v_pk_mul_f32 v[102:103], v[102:103], v[120:121] op_sel_hi:[1,0]
	v_pk_mul_f32 v[98:99], v[98:99], v[120:121] op_sel_hi:[1,0]
	v_add_f32_e32 v119, 1.0, v119
	v_rcp_f32_e32 v122, v119
	v_mul_f32_e32 v119, 0xbfb8aa3b, v111
	v_exp_f32_e32 v119, v119
	v_pk_mul_f32 v[100:101], v[100:101], v[120:121] op_sel_hi:[1,0]
	v_add_f32_e32 v119, 1.0, v119
	v_rcp_f32_e32 v123, v119
	s_nop 0
	v_pk_mul_f32 v[110:111], v[110:111], v[122:123]
	s_nop 0
	v_pk_mul_f32 v[106:107], v[106:107], v[110:111]
	v_pk_mul_f32 v[110:111], v[112:113], v[120:121] op_sel_hi:[1,0]
	s_nop 0
	v_mul_f32_e32 v112, 0xbfb8aa3b, v110
	v_mul_f32_e32 v113, 0xbfb8aa3b, v111
	v_exp_f32_e32 v112, v112
	v_exp_f32_e32 v113, v113
	v_add_f32_e32 v112, 1.0, v112
	v_add_f32_e32 v113, 1.0, v113
	v_rcp_f32_e32 v112, v112
	v_rcp_f32_e32 v113, v113
	s_nop 0
	v_pk_mul_f32 v[110:111], v[110:111], v[112:113]
	s_nop 0
	v_pk_mul_f32 v[108:109], v[108:109], v[110:111]
	v_mul_f32_e32 v110, 0xbfb8aa3b, v102
	v_mul_f32_e32 v111, 0xbfb8aa3b, v103
	v_exp_f32_e32 v110, v110
	v_exp_f32_e32 v111, v111
	v_add_f32_e32 v110, 1.0, v110
	v_add_f32_e32 v111, 1.0, v111
	v_rcp_f32_e32 v110, v110
	v_rcp_f32_e32 v111, v111
	s_nop 0
	v_pk_mul_f32 v[102:103], v[102:103], v[110:111]
	s_nop 0
	v_pk_mul_f32 v[102:103], v[98:99], v[102:103]
	v_pk_mul_f32 v[98:99], v[104:105], v[120:121] op_sel_hi:[1,0]
	s_nop 0
	v_mul_f32_e32 v104, 0xbfb8aa3b, v98
	v_mul_f32_e32 v105, 0xbfb8aa3b, v99
	v_exp_f32_e32 v104, v104
	v_exp_f32_e32 v105, v105
	v_add_f32_e32 v104, 1.0, v104
	v_add_f32_e32 v105, 1.0, v105
	v_rcp_f32_e32 v104, v104
	v_rcp_f32_e32 v105, v105
	s_nop 0
	v_pk_mul_f32 v[98:99], v[98:99], v[104:105]
	s_nop 0
	v_pk_mul_f32 v[104:105], v[100:101], v[98:99]
	v_cvt_pk_bf16_f32 v100, v102, v103
	v_add_u32_e32 v102, s2, v144
	v_mad_i64_i32 v[102:103], s[24:25], v102, s63, v[114:115]
	v_cvt_pk_bf16_f32 v98, v106, v107
	v_cvt_pk_bf16_f32 v99, v108, v109
	v_cvt_pk_bf16_f32 v101, v104, v105
	v_lshl_add_u64 v[102:103], v[102:103], 0, v[116:117]
	global_store_dwordx4 v[102:103], v[98:101], off sc1
	ds_read2_b32 v[98:99], v150 offset0:32 offset1:48
	s_waitcnt lgkmcnt(0)
	v_pk_mul_f32 v[94:95], v[94:95], v[98:99] op_sel_hi:[1,0]
	s_nop 0
	v_mul_f32_e32 v100, 0xbfb8aa3b, v94
	v_mul_f32_e32 v101, 0xbfb8aa3b, v95
	v_exp_f32_e32 v100, v100
	v_exp_f32_e32 v101, v101
	v_pk_mul_f32 v[90:91], v[90:91], v[98:99] op_sel_hi:[1,0]
	v_pk_mul_f32 v[92:93], v[92:93], v[98:99] op_sel_hi:[1,0]
	v_add_f32_e32 v100, 1.0, v100
	v_add_f32_e32 v101, 1.0, v101
	v_rcp_f32_e32 v100, v100
	v_rcp_f32_e32 v101, v101
	v_pk_mul_f32 v[86:87], v[86:87], v[98:99] op_sel_hi:[1,0]
	v_pk_mul_f32 v[82:83], v[82:83], v[98:99] op_sel_hi:[1,0]
	v_pk_mul_f32 v[84:85], v[84:85], v[98:99] op_sel_hi:[1,0]
	v_pk_mul_f32 v[94:95], v[94:95], v[100:101]
	s_nop 0
	v_pk_mul_f32 v[90:91], v[90:91], v[94:95]
	v_pk_mul_f32 v[94:95], v[96:97], v[98:99] op_sel_hi:[1,0]
	s_nop 0
	v_mul_f32_e32 v96, 0xbfb8aa3b, v94
	v_mul_f32_e32 v97, 0xbfb8aa3b, v95
	v_exp_f32_e32 v96, v96
	v_exp_f32_e32 v97, v97
	v_add_f32_e32 v96, 1.0, v96
	v_add_f32_e32 v97, 1.0, v97
	v_rcp_f32_e32 v96, v96
	v_rcp_f32_e32 v97, v97
	s_nop 0
	v_pk_mul_f32 v[94:95], v[94:95], v[96:97]
	s_nop 0
	v_pk_mul_f32 v[92:93], v[92:93], v[94:95]
	v_mul_f32_e32 v94, 0xbfb8aa3b, v86
	v_mul_f32_e32 v95, 0xbfb8aa3b, v87
	v_exp_f32_e32 v94, v94
	v_exp_f32_e32 v95, v95
	v_add_f32_e32 v94, 1.0, v94
	v_add_f32_e32 v95, 1.0, v95
	v_rcp_f32_e32 v94, v94
	v_rcp_f32_e32 v95, v95
	s_nop 0
	v_pk_mul_f32 v[86:87], v[86:87], v[94:95]
	s_nop 0
	v_pk_mul_f32 v[86:87], v[82:83], v[86:87]
	v_pk_mul_f32 v[82:83], v[88:89], v[98:99] op_sel_hi:[1,0]
	s_nop 0
	v_mul_f32_e32 v88, 0xbfb8aa3b, v82
	v_mul_f32_e32 v89, 0xbfb8aa3b, v83
	v_exp_f32_e32 v88, v88
	v_exp_f32_e32 v89, v89
	v_add_f32_e32 v88, 1.0, v88
	v_add_f32_e32 v89, 1.0, v89
	v_rcp_f32_e32 v88, v88
	v_rcp_f32_e32 v89, v89
	s_nop 0
	v_pk_mul_f32 v[82:83], v[82:83], v[88:89]
	s_nop 0
	v_pk_mul_f32 v[88:89], v[84:85], v[82:83]
	v_cvt_pk_bf16_f32 v84, v86, v87
	v_add_u32_e32 v86, s2, v145
	v_mad_i64_i32 v[86:87], s[24:25], v86, s63, v[114:115]
	v_cvt_pk_bf16_f32 v82, v90, v91
	v_cvt_pk_bf16_f32 v83, v92, v93
	v_cvt_pk_bf16_f32 v85, v88, v89
	v_lshl_add_u64 v[86:87], v[86:87], 0, v[116:117]
	global_store_dwordx4 v[86:87], v[82:85], off sc1
	s_mov_b64 s[24:25], -1
	s_nop 0
	v_mov_b32_e32 v82, v99
	v_pk_mul_f32 v[78:79], v[78:79], v[82:83] op_sel_hi:[1,0]
	s_nop 0
	v_mul_f32_e32 v83, 0xbfb8aa3b, v78
	v_exp_f32_e32 v83, v83
	s_nop 0
	v_add_f32_e32 v83, 1.0, v83
	v_rcp_f32_e32 v84, v83
	v_mul_f32_e32 v83, 0xbfb8aa3b, v79
	v_exp_f32_e32 v83, v83
	s_nop 0
	v_add_f32_e32 v83, 1.0, v83
	v_rcp_f32_e32 v85, v83
	v_pk_mul_f32 v[74:75], v[74:75], v[82:83] op_sel_hi:[1,0]
	v_pk_mul_f32 v[76:77], v[76:77], v[82:83] op_sel_hi:[1,0]
	v_pk_mul_f32 v[70:71], v[70:71], v[82:83] op_sel_hi:[1,0]
	v_pk_mul_f32 v[78:79], v[78:79], v[84:85]
	v_pk_mul_f32 v[66:67], v[66:67], v[82:83] op_sel_hi:[1,0]
	v_pk_mul_f32 v[74:75], v[74:75], v[78:79]
	v_pk_mul_f32 v[78:79], v[80:81], v[82:83] op_sel_hi:[1,0]
	v_pk_mul_f32 v[68:69], v[68:69], v[82:83] op_sel_hi:[1,0]
	v_mul_f32_e32 v80, 0xbfb8aa3b, v78
	v_mul_f32_e32 v81, 0xbfb8aa3b, v79
	v_exp_f32_e32 v80, v80
	v_exp_f32_e32 v81, v81
	v_add_f32_e32 v80, 1.0, v80
	v_add_f32_e32 v81, 1.0, v81
	v_rcp_f32_e32 v80, v80
	v_rcp_f32_e32 v81, v81
	s_nop 0
	v_pk_mul_f32 v[78:79], v[78:79], v[80:81]
	s_nop 0
	v_pk_mul_f32 v[76:77], v[76:77], v[78:79]
	v_mul_f32_e32 v78, 0xbfb8aa3b, v70
	v_mul_f32_e32 v79, 0xbfb8aa3b, v71
	v_exp_f32_e32 v78, v78
	v_exp_f32_e32 v79, v79
	v_add_f32_e32 v78, 1.0, v78
	v_add_f32_e32 v79, 1.0, v79
	v_rcp_f32_e32 v78, v78
	v_rcp_f32_e32 v79, v79
	s_nop 0
	v_pk_mul_f32 v[70:71], v[70:71], v[78:79]
	s_nop 0
	v_pk_mul_f32 v[70:71], v[66:67], v[70:71]
	v_pk_mul_f32 v[66:67], v[72:73], v[82:83] op_sel_hi:[1,0]
	s_nop 0
	v_mul_f32_e32 v72, 0xbfb8aa3b, v66
	v_mul_f32_e32 v73, 0xbfb8aa3b, v67
	v_exp_f32_e32 v72, v72
	v_exp_f32_e32 v73, v73
	v_add_f32_e32 v72, 1.0, v72
	v_add_f32_e32 v73, 1.0, v73
	v_rcp_f32_e32 v72, v72
	v_rcp_f32_e32 v73, v73
	s_nop 0
	v_pk_mul_f32 v[66:67], v[66:67], v[72:73]
	s_nop 0
	v_pk_mul_f32 v[72:73], v[68:69], v[66:67]
	v_cvt_pk_bf16_f32 v68, v70, v71
	v_add_u32_e32 v70, s2, v146
	v_mad_i64_i32 v[70:71], s[2:3], v70, s63, v[114:115]
	v_cvt_pk_bf16_f32 v66, v74, v75
	v_cvt_pk_bf16_f32 v67, v76, v77
	v_cvt_pk_bf16_f32 v69, v72, v73
	v_lshl_add_u64 v[70:71], v[70:71], 0, v[116:117]
	global_store_dwordx4 v[70:71], v[66:69], off sc1
	ds_read2_b32 v[66:67], v150 offset0:128 offset1:144
	s_waitcnt lgkmcnt(0)
	v_pk_mul_f32 v[62:63], v[62:63], v[66:67] op_sel_hi:[1,0]
	s_nop 0
	v_mul_f32_e32 v68, 0xbfb8aa3b, v62
	v_mul_f32_e32 v69, 0xbfb8aa3b, v63
	v_exp_f32_e32 v68, v68
	v_exp_f32_e32 v69, v69
	v_pk_mul_f32 v[58:59], v[58:59], v[66:67] op_sel_hi:[1,0]
	v_pk_mul_f32 v[60:61], v[60:61], v[66:67] op_sel_hi:[1,0]
	v_add_f32_e32 v68, 1.0, v68
	v_add_f32_e32 v69, 1.0, v69
	v_rcp_f32_e32 v68, v68
	v_rcp_f32_e32 v69, v69
	v_pk_mul_f32 v[54:55], v[54:55], v[66:67] op_sel_hi:[1,0]
	v_pk_mul_f32 v[50:51], v[50:51], v[66:67] op_sel_hi:[1,0]
	v_pk_mul_f32 v[52:53], v[52:53], v[66:67] op_sel_hi:[1,0]
	v_pk_mul_f32 v[62:63], v[62:63], v[68:69]
	s_nop 0
	v_pk_mul_f32 v[58:59], v[58:59], v[62:63]
	v_pk_mul_f32 v[62:63], v[64:65], v[66:67] op_sel_hi:[1,0]
	s_nop 0
	v_mul_f32_e32 v64, 0xbfb8aa3b, v62
	v_mul_f32_e32 v65, 0xbfb8aa3b, v63
	v_exp_f32_e32 v64, v64
	v_exp_f32_e32 v65, v65
	v_add_f32_e32 v64, 1.0, v64
	v_add_f32_e32 v65, 1.0, v65
	v_rcp_f32_e32 v64, v64
	v_rcp_f32_e32 v65, v65
	s_nop 0
	v_pk_mul_f32 v[62:63], v[62:63], v[64:65]
	s_nop 0
	v_pk_mul_f32 v[60:61], v[60:61], v[62:63]
	v_mul_f32_e32 v62, 0xbfb8aa3b, v54
	v_mul_f32_e32 v63, 0xbfb8aa3b, v55
	v_exp_f32_e32 v62, v62
	v_exp_f32_e32 v63, v63
	v_add_f32_e32 v62, 1.0, v62
	v_add_f32_e32 v63, 1.0, v63
	v_rcp_f32_e32 v62, v62
	v_rcp_f32_e32 v63, v63
	s_nop 0
	v_pk_mul_f32 v[54:55], v[54:55], v[62:63]
	s_nop 0
	v_pk_mul_f32 v[54:55], v[50:51], v[54:55]
	v_pk_mul_f32 v[50:51], v[56:57], v[66:67] op_sel_hi:[1,0]
	s_nop 0
	v_mul_f32_e32 v56, 0xbfb8aa3b, v50
	v_mul_f32_e32 v57, 0xbfb8aa3b, v51
	v_exp_f32_e32 v56, v56
	v_exp_f32_e32 v57, v57
	v_add_f32_e32 v56, 1.0, v56
	v_add_f32_e32 v57, 1.0, v57
	v_rcp_f32_e32 v56, v56
	v_rcp_f32_e32 v57, v57
	s_nop 0
	v_pk_mul_f32 v[50:51], v[50:51], v[56:57]
	s_nop 0
	v_pk_mul_f32 v[56:57], v[52:53], v[50:51]
	v_cvt_pk_bf16_f32 v52, v54, v55
	v_add_u32_e32 v54, 0x80, v118
	v_mad_i64_i32 v[54:55], s[2:3], v54, s63, v[114:115]
	v_cvt_pk_bf16_f32 v50, v58, v59
	v_cvt_pk_bf16_f32 v51, v60, v61
	v_cvt_pk_bf16_f32 v53, v56, v57
	v_lshl_add_u64 v[54:55], v[54:55], 0, v[116:117]
	global_store_dwordx4 v[54:55], v[50:53], off sc1
	s_nop 1
	v_mov_b32_e32 v50, v67
	v_pk_mul_f32 v[46:47], v[46:47], v[50:51] op_sel_hi:[1,0]
	s_nop 0
	v_mul_f32_e32 v51, 0xbfb8aa3b, v46
	v_exp_f32_e32 v51, v51
	s_nop 0
	v_add_f32_e32 v51, 1.0, v51
	v_rcp_f32_e32 v52, v51
	v_mul_f32_e32 v51, 0xbfb8aa3b, v47
	v_exp_f32_e32 v51, v51
	s_nop 0
	v_add_f32_e32 v51, 1.0, v51
	v_rcp_f32_e32 v53, v51
	v_pk_mul_f32 v[42:43], v[42:43], v[50:51] op_sel_hi:[1,0]
	v_pk_mul_f32 v[44:45], v[44:45], v[50:51] op_sel_hi:[1,0]
	v_pk_mul_f32 v[38:39], v[38:39], v[50:51] op_sel_hi:[1,0]
	v_pk_mul_f32 v[46:47], v[46:47], v[52:53]
	v_pk_mul_f32 v[34:35], v[34:35], v[50:51] op_sel_hi:[1,0]
	v_pk_mul_f32 v[42:43], v[42:43], v[46:47]
	v_pk_mul_f32 v[46:47], v[48:49], v[50:51] op_sel_hi:[1,0]
	v_pk_mul_f32 v[36:37], v[36:37], v[50:51] op_sel_hi:[1,0]
	v_mul_f32_e32 v48, 0xbfb8aa3b, v46
	v_mul_f32_e32 v49, 0xbfb8aa3b, v47
	v_exp_f32_e32 v48, v48
	v_exp_f32_e32 v49, v49
	v_add_f32_e32 v48, 1.0, v48
	v_add_f32_e32 v49, 1.0, v49
	v_rcp_f32_e32 v48, v48
	v_rcp_f32_e32 v49, v49
	s_nop 0
	v_pk_mul_f32 v[46:47], v[46:47], v[48:49]
	s_nop 0
	v_pk_mul_f32 v[44:45], v[44:45], v[46:47]
	v_mul_f32_e32 v46, 0xbfb8aa3b, v38
	v_mul_f32_e32 v47, 0xbfb8aa3b, v39
	v_exp_f32_e32 v46, v46
	v_exp_f32_e32 v47, v47
	v_add_f32_e32 v46, 1.0, v46
	v_add_f32_e32 v47, 1.0, v47
	v_rcp_f32_e32 v46, v46
	v_rcp_f32_e32 v47, v47
	s_nop 0
	v_pk_mul_f32 v[38:39], v[38:39], v[46:47]
	s_nop 0
	v_pk_mul_f32 v[38:39], v[34:35], v[38:39]
	v_pk_mul_f32 v[34:35], v[40:41], v[50:51] op_sel_hi:[1,0]
	s_nop 0
	v_mul_f32_e32 v40, 0xbfb8aa3b, v34
	v_mul_f32_e32 v41, 0xbfb8aa3b, v35
	v_exp_f32_e32 v40, v40
	v_exp_f32_e32 v41, v41
	v_add_f32_e32 v40, 1.0, v40
	v_add_f32_e32 v41, 1.0, v41
	v_rcp_f32_e32 v40, v40
	v_rcp_f32_e32 v41, v41
	s_nop 0
	v_pk_mul_f32 v[34:35], v[34:35], v[40:41]
	s_nop 0
	v_pk_mul_f32 v[40:41], v[36:37], v[34:35]
	v_cvt_pk_bf16_f32 v36, v38, v39
	v_add_u32_e32 v38, 0x90, v118
	v_mad_i64_i32 v[38:39], s[2:3], v38, s63, v[114:115]
	v_cvt_pk_bf16_f32 v34, v42, v43
	v_cvt_pk_bf16_f32 v35, v44, v45
	v_cvt_pk_bf16_f32 v37, v40, v41
	v_lshl_add_u64 v[38:39], v[38:39], 0, v[116:117]
	global_store_dwordx4 v[38:39], v[34:37], off sc1
	ds_read2_b32 v[34:35], v150 offset0:160 offset1:176
	s_waitcnt lgkmcnt(0)
	v_pk_mul_f32 v[30:31], v[30:31], v[34:35] op_sel_hi:[1,0]
	s_nop 0
	v_mul_f32_e32 v36, 0xbfb8aa3b, v30
	v_mul_f32_e32 v37, 0xbfb8aa3b, v31
	v_exp_f32_e32 v36, v36
	v_exp_f32_e32 v37, v37
	v_pk_mul_f32 v[26:27], v[26:27], v[34:35] op_sel_hi:[1,0]
	v_pk_mul_f32 v[28:29], v[28:29], v[34:35] op_sel_hi:[1,0]
	v_add_f32_e32 v36, 1.0, v36
	v_add_f32_e32 v37, 1.0, v37
	v_rcp_f32_e32 v36, v36
	v_rcp_f32_e32 v37, v37
	v_pk_mul_f32 v[22:23], v[22:23], v[34:35] op_sel_hi:[1,0]
	v_pk_mul_f32 v[18:19], v[18:19], v[34:35] op_sel_hi:[1,0]
	v_pk_mul_f32 v[20:21], v[20:21], v[34:35] op_sel_hi:[1,0]
	v_pk_mul_f32 v[30:31], v[30:31], v[36:37]
	s_nop 0
	v_pk_mul_f32 v[26:27], v[26:27], v[30:31]
	v_pk_mul_f32 v[30:31], v[32:33], v[34:35] op_sel_hi:[1,0]
	s_nop 0
	v_mul_f32_e32 v32, 0xbfb8aa3b, v30
	v_mul_f32_e32 v33, 0xbfb8aa3b, v31
	v_exp_f32_e32 v32, v32
	v_exp_f32_e32 v33, v33
	v_add_f32_e32 v32, 1.0, v32
	v_add_f32_e32 v33, 1.0, v33
	v_rcp_f32_e32 v32, v32
	v_rcp_f32_e32 v33, v33
	s_nop 0
	v_pk_mul_f32 v[30:31], v[30:31], v[32:33]
	s_nop 0
	v_pk_mul_f32 v[28:29], v[28:29], v[30:31]
	v_mul_f32_e32 v30, 0xbfb8aa3b, v22
	v_mul_f32_e32 v31, 0xbfb8aa3b, v23
	v_exp_f32_e32 v30, v30
	v_exp_f32_e32 v31, v31
	v_add_f32_e32 v30, 1.0, v30
	v_add_f32_e32 v31, 1.0, v31
	v_rcp_f32_e32 v30, v30
	v_rcp_f32_e32 v31, v31
	s_nop 0
	v_pk_mul_f32 v[22:23], v[22:23], v[30:31]
	s_nop 0
	v_pk_mul_f32 v[22:23], v[18:19], v[22:23]
	v_pk_mul_f32 v[18:19], v[24:25], v[34:35] op_sel_hi:[1,0]
	s_nop 0
	v_mul_f32_e32 v24, 0xbfb8aa3b, v18
	v_mul_f32_e32 v25, 0xbfb8aa3b, v19
	v_exp_f32_e32 v24, v24
	v_exp_f32_e32 v25, v25
	v_add_f32_e32 v24, 1.0, v24
	v_add_f32_e32 v25, 1.0, v25
	v_rcp_f32_e32 v24, v24
	v_rcp_f32_e32 v25, v25
	s_nop 0
	v_pk_mul_f32 v[18:19], v[18:19], v[24:25]
	s_nop 0
	v_pk_mul_f32 v[24:25], v[20:21], v[18:19]
	v_cvt_pk_bf16_f32 v20, v22, v23
	v_add_u32_e32 v22, 0xa0, v118
	v_mad_i64_i32 v[22:23], s[2:3], v22, s63, v[114:115]
	v_cvt_pk_bf16_f32 v18, v26, v27
	v_cvt_pk_bf16_f32 v19, v28, v29
	v_cvt_pk_bf16_f32 v21, v24, v25
	v_lshl_add_u64 v[22:23], v[22:23], 0, v[116:117]
	global_store_dwordx4 v[22:23], v[18:21], off sc1
	s_nop 1
	v_mov_b32_e32 v18, v35
	v_pk_mul_f32 v[14:15], v[14:15], v[18:19] op_sel_hi:[1,0]
	s_nop 0
	v_mul_f32_e32 v19, 0xbfb8aa3b, v14
	v_exp_f32_e32 v19, v19
	s_nop 0
	v_add_f32_e32 v19, 1.0, v19
	v_rcp_f32_e32 v20, v19
	v_mul_f32_e32 v19, 0xbfb8aa3b, v15
	v_exp_f32_e32 v19, v19
	s_nop 0
	v_add_f32_e32 v19, 1.0, v19
	v_rcp_f32_e32 v21, v19
	v_pk_mul_f32 v[10:11], v[10:11], v[18:19] op_sel_hi:[1,0]
	v_pk_mul_f32 v[12:13], v[12:13], v[18:19] op_sel_hi:[1,0]
	v_pk_mul_f32 v[6:7], v[6:7], v[18:19] op_sel_hi:[1,0]
	v_pk_mul_f32 v[14:15], v[14:15], v[20:21]
	v_pk_mul_f32 v[2:3], v[2:3], v[18:19] op_sel_hi:[1,0]
	v_pk_mul_f32 v[10:11], v[10:11], v[14:15]
	v_pk_mul_f32 v[14:15], v[16:17], v[18:19] op_sel_hi:[1,0]
	v_pk_mul_f32 v[4:5], v[4:5], v[18:19] op_sel_hi:[1,0]
	v_mul_f32_e32 v16, 0xbfb8aa3b, v14
	v_mul_f32_e32 v17, 0xbfb8aa3b, v15
	v_exp_f32_e32 v16, v16
	v_exp_f32_e32 v17, v17
	v_add_f32_e32 v16, 1.0, v16
	v_add_f32_e32 v17, 1.0, v17
	v_rcp_f32_e32 v16, v16
	v_rcp_f32_e32 v17, v17
	s_nop 0
	v_pk_mul_f32 v[14:15], v[14:15], v[16:17]
	s_nop 0
	v_pk_mul_f32 v[12:13], v[12:13], v[14:15]
	v_mul_f32_e32 v14, 0xbfb8aa3b, v6
	v_mul_f32_e32 v15, 0xbfb8aa3b, v7
	v_exp_f32_e32 v14, v14
	v_exp_f32_e32 v15, v15
	v_add_f32_e32 v14, 1.0, v14
	v_add_f32_e32 v15, 1.0, v15
	v_rcp_f32_e32 v14, v14
	v_rcp_f32_e32 v15, v15
	s_nop 0
	v_pk_mul_f32 v[6:7], v[6:7], v[14:15]
	s_nop 0
	v_pk_mul_f32 v[6:7], v[2:3], v[6:7]
	v_pk_mul_f32 v[2:3], v[8:9], v[18:19] op_sel_hi:[1,0]
	s_nop 0
	v_mul_f32_e32 v8, 0xbfb8aa3b, v2
	v_mul_f32_e32 v9, 0xbfb8aa3b, v3
	v_exp_f32_e32 v8, v8
	v_exp_f32_e32 v9, v9
	v_add_f32_e32 v8, 1.0, v8
	v_add_f32_e32 v9, 1.0, v9
	v_rcp_f32_e32 v8, v8
	v_rcp_f32_e32 v9, v9
	s_nop 0
	v_pk_mul_f32 v[2:3], v[2:3], v[8:9]
	s_nop 0
	v_pk_mul_f32 v[8:9], v[4:5], v[2:3]
	v_cvt_pk_bf16_f32 v4, v6, v7
	v_add_u32_e32 v6, 0xb0, v118
	v_mad_i64_i32 v[6:7], s[2:3], v6, s63, v[114:115]
	v_cvt_pk_bf16_f32 v2, v10, v11
	v_cvt_pk_bf16_f32 v3, v12, v13
	v_cvt_pk_bf16_f32 v5, v8, v9
	v_lshl_add_u64 v[6:7], v[6:7], 0, v[116:117]
	global_store_dwordx4 v[6:7], v[2:5], off sc1
	s_cbranch_vccnz .LBB0_1093
	s_andn2_b64 vcc, exec, s[8:9]
	s_cbranch_vccnz .LBB0_1092
	s_barrier
	s_branch .LBB0_1092

.LBB0_1200:
	s_ashr_i32 s29, s28, 31
	v_lshl_or_b32 v180, s50, 8, v205
	s_lshl_b64 s[2:3], s[28:29], 8
	v_lshl_add_u64 v[182:183], s[2:3], 0, v[164:165]
	v_ashrrev_i32_e32 v181, 31, v180
	v_lshl_add_u64 v[184:185], v[180:181], 1, s[16:17]
	v_lshlrev_b64 v[200:201], 11, v[182:183]
	v_or_b32_e32 v196, 16, v182
	v_mov_b32_e32 v197, v183
	v_lshl_add_u64 v[130:131], v[184:185], 0, v[200:201]
	v_lshlrev_b64 v[194:195], 11, v[196:197]
	v_or_b32_e32 v192, 32, v182
	v_mov_b32_e32 v193, v183
	global_load_dwordx4 v[208:211], v[130:131], off
	global_load_dwordx4 v[154:157], v[130:131], off offset:256
	v_lshl_add_u64 v[130:131], v[184:185], 0, v[194:195]
	v_lshlrev_b64 v[190:191], 11, v[192:193]
	v_or_b32_e32 v188, 48, v182
	v_mov_b32_e32 v189, v183
	global_load_dwordx4 v[150:153], v[130:131], off
	global_load_dwordx4 v[146:149], v[130:131], off offset:256
	v_lshl_add_u64 v[130:131], v[184:185], 0, v[190:191]
	v_lshlrev_b64 v[186:187], 11, v[188:189]
	global_load_dwordx4 v[142:145], v[130:131], off
	global_load_dwordx4 v[138:141], v[130:131], off offset:256
	v_lshl_add_u64 v[130:131], v[184:185], 0, v[186:187]
	global_load_dwordx4 v[134:137], v[130:131], off
	s_nop 0
	global_load_dwordx4 v[130:133], v[130:131], off offset:256
	v_cndmask_b32_e64 v198, 0, 1, s[22:23]
	v_cmp_ne_u32_e64 s[8:9], 1, v198
	v_lshlrev_b64 v[198:199], 12, v[182:183]
	v_lshl_add_u64 v[198:199], s[12:13], 0, v[198:199]
	s_andn2_b64 vcc, exec, s[22:23]
	s_waitcnt vmcnt(0)
	v_lshlrev_b32_e32 v202, 16, v208
	v_and_b32_e32 v203, 0xffff0000, v208
	v_lshlrev_b32_e32 v208, 16, v209
	v_and_b32_e32 v209, 0xffff0000, v209
	v_lshlrev_b32_e32 v212, 16, v210
	v_and_b32_e32 v213, 0xffff0000, v210
	v_lshlrev_b32_e32 v210, 16, v211
	v_and_b32_e32 v211, 0xffff0000, v211
	v_pk_fma_f32 v[128:129], v[128:129], 0.5, v[208:209] op_sel_hi:[1,0,1]
	v_pk_fma_f32 v[126:127], v[126:127], 0.5, v[202:203] op_sel_hi:[1,0,1]
	v_pk_fma_f32 v[124:125], v[124:125], 0.5, v[210:211] op_sel_hi:[1,0,1]
	v_pk_fma_f32 v[122:123], v[122:123], 0.5, v[212:213] op_sel_hi:[1,0,1]
	v_lshl_add_u64 v[202:203], v[180:181], 2, v[198:199]
	s_cbranch_vccnz .LBB0_1202
	s_mov_b64 s[30:31], 0
	global_store_dwordx4 v[202:203], v[126:129], off sc1
	global_store_dwordx4 v[202:203], v[122:125], off offset:16 sc1
	s_branch .LBB0_1203

.LBB0_1203:
	s_lshl_b32 s28, s50, 3
	v_lshl_add_u64 v[200:201], s[16:17], 0, v[200:201]
	s_ashr_i32 s29, s28, 31
	v_lshlrev_b64 v[198:199], 7, v[182:183]
	s_andn2_b64 vcc, exec, s[30:31]
	v_lshl_add_u64 v[200:201], v[180:181], 1, v[200:201]
	s_cbranch_vccnz .LBB0_1207
	v_cvt_pk_bf16_f32 v208, v126, v127
	v_mul_f32_e32 v127, v127, v127
	v_fmac_f32_e32 v127, v126, v126
	v_mul_f32_e32 v126, v129, v129
	v_fmac_f32_e32 v126, v128, v128
	v_add_f32_e32 v126, v127, v126
	v_mul_f32_e32 v127, v123, v123
	v_fmac_f32_e32 v127, v122, v122
	v_add_f32_e32 v126, v127, v126
	v_mul_f32_e32 v127, v125, v125
	v_fmac_f32_e32 v127, v124, v124
	v_add_f32_e32 v126, v127, v126
	ds_swizzle_b32 v127, v126 offset:swizzle(SWAP,16)
	v_cvt_pk_bf16_f32 v210, v122, v123
	v_cvt_pk_bf16_f32 v209, v128, v129
	v_cvt_pk_bf16_f32 v211, v124, v125
	global_store_dwordx4 v[200:201], v[208:211], off sc1
	s_waitcnt lgkmcnt(0)
	v_add_f32_e32 v122, v126, v127
	v_mov_b32_e32 v123, v122
	s_nop 1
	v_permlane32_swap_b32_e32 v122, v123
	s_and_saveexec_b64 s[30:31], s[4:5]
	s_cbranch_execz .LBB0_1206
	v_lshl_add_u64 v[124:125], s[18:19], 0, v[198:199]
	v_lshl_add_u64 v[124:125], s[28:29], 2, v[124:125]
	s_lshl_b32 s50, s57, 2
	v_lshl_add_u64 v[124:125], v[124:125], 0, s[50:51]
	v_add_f32_e32 v122, v122, v123
	global_store_dword v[124:125], v122, off sc1

.LBB0_1207:
	v_lshlrev_b32_e32 v122, 16, v154
	v_and_b32_e32 v123, 0xffff0000, v154
	v_lshlrev_b32_e32 v124, 16, v155
	v_and_b32_e32 v125, 0xffff0000, v155
	v_lshlrev_b32_e32 v126, 16, v156
	v_and_b32_e32 v127, 0xffff0000, v156
	v_lshlrev_b32_e32 v128, 16, v157
	v_and_b32_e32 v129, 0xffff0000, v157
	v_pk_fma_f32 v[120:121], v[120:121], 0.5, v[124:125] op_sel_hi:[1,0,1]
	v_pk_fma_f32 v[118:119], v[118:119], 0.5, v[122:123] op_sel_hi:[1,0,1]
	v_pk_fma_f32 v[116:117], v[116:117], 0.5, v[128:129] op_sel_hi:[1,0,1]
	s_and_b64 vcc, exec, s[8:9]
	v_pk_fma_f32 v[114:115], v[114:115], 0.5, v[126:127] op_sel_hi:[1,0,1]
	s_cbranch_vccnz .LBB0_1209
	global_store_dwordx4 v[202:203], v[118:121], off offset:512 sc1
	global_store_dwordx4 v[202:203], v[114:117], off offset:528 sc1
	s_cbranch_execz .LBB0_1210
	s_branch .LBB0_1213
.LBB0_1209:
.LBB0_1210:
	v_cvt_pk_bf16_f32 v122, v118, v119
	v_mul_f32_e32 v119, v119, v119
	v_fmac_f32_e32 v119, v118, v118
	v_mul_f32_e32 v118, v121, v121
	v_fmac_f32_e32 v118, v120, v120
	v_add_f32_e32 v118, v119, v118
	v_mul_f32_e32 v119, v115, v115
	v_fmac_f32_e32 v119, v114, v114
	v_add_f32_e32 v118, v119, v118
	v_mul_f32_e32 v119, v117, v117
	v_fmac_f32_e32 v119, v116, v116
	v_add_f32_e32 v118, v119, v118
	ds_swizzle_b32 v119, v118 offset:swizzle(SWAP,16)
	v_cvt_pk_bf16_f32 v124, v114, v115
	v_cvt_pk_bf16_f32 v123, v120, v121
	v_cvt_pk_bf16_f32 v125, v116, v117
	global_store_dwordx4 v[200:201], v[122:125], off offset:256 sc1
	s_waitcnt lgkmcnt(0)
	v_add_f32_e32 v114, v118, v119
	v_mov_b32_e32 v115, v114
	s_nop 1
	v_permlane32_swap_b32_e32 v114, v115
	s_and_saveexec_b64 s[30:31], s[4:5]
	s_cbranch_execz .LBB0_1212
	v_lshl_add_u64 v[116:117], s[18:19], 0, v[198:199]
	v_lshl_add_u64 v[116:117], s[28:29], 2, v[116:117]
	s_lshl_b32 s50, s57, 2
	v_lshl_add_u64 v[116:117], v[116:117], 0, s[50:51]
	v_add_f32_e32 v114, v114, v115
	global_store_dword v[116:117], v114, off offset:16 sc1

.LBB0_1213:
	v_lshlrev_b64 v[114:115], 12, v[196:197]
	v_lshlrev_b32_e32 v116, 16, v150
	v_and_b32_e32 v117, 0xffff0000, v150
	v_lshlrev_b32_e32 v118, 16, v151
	v_and_b32_e32 v119, 0xffff0000, v151
	v_lshlrev_b32_e32 v120, 16, v152
	v_and_b32_e32 v121, 0xffff0000, v152
	v_lshlrev_b32_e32 v122, 16, v153
	v_and_b32_e32 v123, 0xffff0000, v153
	v_lshl_add_u64 v[114:115], s[12:13], 0, v[114:115]
	v_pk_fma_f32 v[112:113], v[112:113], 0.5, v[118:119] op_sel_hi:[1,0,1]
	v_pk_fma_f32 v[110:111], v[110:111], 0.5, v[116:117] op_sel_hi:[1,0,1]
	v_pk_fma_f32 v[108:109], v[108:109], 0.5, v[122:123] op_sel_hi:[1,0,1]
	v_pk_fma_f32 v[106:107], v[106:107], 0.5, v[120:121] op_sel_hi:[1,0,1]
	s_and_b64 vcc, exec, s[8:9]
	v_lshl_add_u64 v[118:119], v[180:181], 2, v[114:115]
	s_cbranch_vccnz .LBB0_1215
	s_mov_b64 s[30:31], 0
	global_store_dwordx4 v[118:119], v[110:113], off sc1
	global_store_dwordx4 v[118:119], v[106:109], off offset:16 sc1
	s_branch .LBB0_1216

.LBB0_1216:
	v_lshl_add_u64 v[116:117], s[16:17], 0, v[194:195]
	v_lshlrev_b64 v[114:115], 7, v[196:197]
	s_andn2_b64 vcc, exec, s[30:31]
	v_lshl_add_u64 v[116:117], v[180:181], 1, v[116:117]
	s_cbranch_vccnz .LBB0_1220
	v_cvt_pk_bf16_f32 v120, v110, v111
	v_mul_f32_e32 v111, v111, v111
	v_fmac_f32_e32 v111, v110, v110
	v_mul_f32_e32 v110, v113, v113
	v_fmac_f32_e32 v110, v112, v112
	v_add_f32_e32 v110, v111, v110
	v_mul_f32_e32 v111, v107, v107
	v_fmac_f32_e32 v111, v106, v106
	v_add_f32_e32 v110, v111, v110
	v_mul_f32_e32 v111, v109, v109
	v_fmac_f32_e32 v111, v108, v108
	v_add_f32_e32 v110, v111, v110
	ds_swizzle_b32 v111, v110 offset:swizzle(SWAP,16)
	v_cvt_pk_bf16_f32 v122, v106, v107
	v_cvt_pk_bf16_f32 v121, v112, v113
	v_cvt_pk_bf16_f32 v123, v108, v109
	global_store_dwordx4 v[116:117], v[120:123], off sc1
	s_waitcnt lgkmcnt(0)
	v_add_f32_e32 v106, v110, v111
	v_mov_b32_e32 v107, v106
	s_nop 1
	v_permlane32_swap_b32_e32 v106, v107
	s_and_saveexec_b64 s[30:31], s[4:5]
	s_cbranch_execz .LBB0_1219
	v_lshl_add_u64 v[108:109], s[18:19], 0, v[114:115]
	v_lshl_add_u64 v[108:109], s[28:29], 2, v[108:109]
	s_lshl_b32 s50, s57, 2
	v_lshl_add_u64 v[108:109], v[108:109], 0, s[50:51]
	v_add_f32_e32 v106, v106, v107
	global_store_dword v[108:109], v106, off sc1

.LBB0_1220:
	v_lshlrev_b32_e32 v106, 16, v146
	v_and_b32_e32 v107, 0xffff0000, v146
	v_lshlrev_b32_e32 v108, 16, v147
	v_and_b32_e32 v109, 0xffff0000, v147
	v_lshlrev_b32_e32 v110, 16, v148
	v_and_b32_e32 v111, 0xffff0000, v148
	v_lshlrev_b32_e32 v112, 16, v149
	v_and_b32_e32 v113, 0xffff0000, v149
	v_pk_fma_f32 v[104:105], v[104:105], 0.5, v[108:109] op_sel_hi:[1,0,1]
	v_pk_fma_f32 v[102:103], v[102:103], 0.5, v[106:107] op_sel_hi:[1,0,1]
	v_pk_fma_f32 v[100:101], v[100:101], 0.5, v[112:113] op_sel_hi:[1,0,1]
	s_and_b64 vcc, exec, s[8:9]
	v_pk_fma_f32 v[98:99], v[98:99], 0.5, v[110:111] op_sel_hi:[1,0,1]
	s_cbranch_vccnz .LBB0_1222
	global_store_dwordx4 v[118:119], v[102:105], off offset:512 sc1
	global_store_dwordx4 v[118:119], v[98:101], off offset:528 sc1
	s_cbranch_execz .LBB0_1223
	s_branch .LBB0_1226
.LBB0_1222:
.LBB0_1223:
	v_cvt_pk_bf16_f32 v106, v102, v103
	v_mul_f32_e32 v103, v103, v103
	v_fmac_f32_e32 v103, v102, v102
	v_mul_f32_e32 v102, v105, v105
	v_fmac_f32_e32 v102, v104, v104
	v_add_f32_e32 v102, v103, v102
	v_mul_f32_e32 v103, v99, v99
	v_fmac_f32_e32 v103, v98, v98
	v_add_f32_e32 v102, v103, v102
	v_mul_f32_e32 v103, v101, v101
	v_fmac_f32_e32 v103, v100, v100
	v_add_f32_e32 v102, v103, v102
	ds_swizzle_b32 v103, v102 offset:swizzle(SWAP,16)
	v_cvt_pk_bf16_f32 v108, v98, v99
	v_cvt_pk_bf16_f32 v107, v104, v105
	v_cvt_pk_bf16_f32 v109, v100, v101
	global_store_dwordx4 v[116:117], v[106:109], off offset:256 sc1
	s_waitcnt lgkmcnt(0)
	v_add_f32_e32 v98, v102, v103
	v_mov_b32_e32 v99, v98
	s_nop 1
	v_permlane32_swap_b32_e32 v98, v99
	s_and_saveexec_b64 s[30:31], s[4:5]
	s_cbranch_execz .LBB0_1225
	v_lshl_add_u64 v[100:101], s[18:19], 0, v[114:115]
	v_lshl_add_u64 v[100:101], s[28:29], 2, v[100:101]
	s_lshl_b32 s50, s57, 2
	v_lshl_add_u64 v[100:101], v[100:101], 0, s[50:51]
	v_add_f32_e32 v98, v98, v99
	global_store_dword v[100:101], v98, off offset:16 sc1

.LBB0_1226:
	v_lshlrev_b64 v[98:99], 12, v[192:193]
	v_lshlrev_b32_e32 v100, 16, v142
	v_and_b32_e32 v101, 0xffff0000, v142
	v_lshlrev_b32_e32 v102, 16, v143
	v_and_b32_e32 v103, 0xffff0000, v143
	v_lshlrev_b32_e32 v104, 16, v144
	v_and_b32_e32 v105, 0xffff0000, v144
	v_lshlrev_b32_e32 v106, 16, v145
	v_and_b32_e32 v107, 0xffff0000, v145
	v_lshl_add_u64 v[98:99], s[12:13], 0, v[98:99]
	v_pk_fma_f32 v[96:97], v[96:97], 0.5, v[102:103] op_sel_hi:[1,0,1]
	v_pk_fma_f32 v[94:95], v[94:95], 0.5, v[100:101] op_sel_hi:[1,0,1]
	v_pk_fma_f32 v[92:93], v[92:93], 0.5, v[106:107] op_sel_hi:[1,0,1]
	v_pk_fma_f32 v[90:91], v[90:91], 0.5, v[104:105] op_sel_hi:[1,0,1]
	s_and_b64 vcc, exec, s[8:9]
	v_lshl_add_u64 v[102:103], v[180:181], 2, v[98:99]
	s_cbranch_vccnz .LBB0_1228
	s_mov_b64 s[30:31], 0
	global_store_dwordx4 v[102:103], v[94:97], off sc1
	global_store_dwordx4 v[102:103], v[90:93], off offset:16 sc1
	s_branch .LBB0_1229

.LBB0_1229:
	v_lshl_add_u64 v[100:101], s[16:17], 0, v[190:191]
	v_lshlrev_b64 v[98:99], 7, v[192:193]
	s_andn2_b64 vcc, exec, s[30:31]
	v_lshl_add_u64 v[100:101], v[180:181], 1, v[100:101]
	s_cbranch_vccnz .LBB0_1233
	v_cvt_pk_bf16_f32 v104, v94, v95
	v_mul_f32_e32 v95, v95, v95
	v_fmac_f32_e32 v95, v94, v94
	v_mul_f32_e32 v94, v97, v97
	v_fmac_f32_e32 v94, v96, v96
	v_add_f32_e32 v94, v95, v94
	v_mul_f32_e32 v95, v91, v91
	v_fmac_f32_e32 v95, v90, v90
	v_add_f32_e32 v94, v95, v94
	v_mul_f32_e32 v95, v93, v93
	v_fmac_f32_e32 v95, v92, v92
	v_add_f32_e32 v94, v95, v94
	ds_swizzle_b32 v95, v94 offset:swizzle(SWAP,16)
	v_cvt_pk_bf16_f32 v106, v90, v91
	v_cvt_pk_bf16_f32 v105, v96, v97
	v_cvt_pk_bf16_f32 v107, v92, v93
	global_store_dwordx4 v[100:101], v[104:107], off sc1
	s_waitcnt lgkmcnt(0)
	v_add_f32_e32 v90, v94, v95
	v_mov_b32_e32 v91, v90
	s_nop 1
	v_permlane32_swap_b32_e32 v90, v91
	s_and_saveexec_b64 s[30:31], s[4:5]
	s_cbranch_execz .LBB0_1232
	v_lshl_add_u64 v[92:93], s[18:19], 0, v[98:99]
	v_lshl_add_u64 v[92:93], s[28:29], 2, v[92:93]
	s_lshl_b32 s50, s57, 2
	v_lshl_add_u64 v[92:93], v[92:93], 0, s[50:51]
	v_add_f32_e32 v90, v90, v91
	global_store_dword v[92:93], v90, off sc1

.LBB0_1233:
	v_lshlrev_b32_e32 v90, 16, v138
	v_and_b32_e32 v91, 0xffff0000, v138
	v_lshlrev_b32_e32 v92, 16, v139
	v_and_b32_e32 v93, 0xffff0000, v139
	v_lshlrev_b32_e32 v94, 16, v140
	v_and_b32_e32 v95, 0xffff0000, v140
	v_lshlrev_b32_e32 v96, 16, v141
	v_and_b32_e32 v97, 0xffff0000, v141
	v_pk_fma_f32 v[88:89], v[88:89], 0.5, v[92:93] op_sel_hi:[1,0,1]
	v_pk_fma_f32 v[86:87], v[86:87], 0.5, v[90:91] op_sel_hi:[1,0,1]
	v_pk_fma_f32 v[84:85], v[84:85], 0.5, v[96:97] op_sel_hi:[1,0,1]
	s_and_b64 vcc, exec, s[8:9]
	v_pk_fma_f32 v[82:83], v[82:83], 0.5, v[94:95] op_sel_hi:[1,0,1]
	s_cbranch_vccnz .LBB0_1235
	global_store_dwordx4 v[102:103], v[86:89], off offset:512 sc1
	global_store_dwordx4 v[102:103], v[82:85], off offset:528 sc1
	s_cbranch_execz .LBB0_1236
	s_branch .LBB0_1239
.LBB0_1235:
.LBB0_1236:
	v_cvt_pk_bf16_f32 v90, v86, v87
	v_mul_f32_e32 v87, v87, v87
	v_fmac_f32_e32 v87, v86, v86
	v_mul_f32_e32 v86, v89, v89
	v_fmac_f32_e32 v86, v88, v88
	v_add_f32_e32 v86, v87, v86
	v_mul_f32_e32 v87, v83, v83
	v_fmac_f32_e32 v87, v82, v82
	v_add_f32_e32 v86, v87, v86
	v_mul_f32_e32 v87, v85, v85
	v_fmac_f32_e32 v87, v84, v84
	v_add_f32_e32 v86, v87, v86
	ds_swizzle_b32 v87, v86 offset:swizzle(SWAP,16)
	v_cvt_pk_bf16_f32 v92, v82, v83
	v_cvt_pk_bf16_f32 v91, v88, v89
	v_cvt_pk_bf16_f32 v93, v84, v85
	global_store_dwordx4 v[100:101], v[90:93], off offset:256 sc1
	s_waitcnt lgkmcnt(0)
	v_add_f32_e32 v82, v86, v87
	v_mov_b32_e32 v83, v82
	s_nop 1
	v_permlane32_swap_b32_e32 v82, v83
	s_and_saveexec_b64 s[30:31], s[4:5]
	s_cbranch_execz .LBB0_1238
	v_lshl_add_u64 v[84:85], s[18:19], 0, v[98:99]
	v_lshl_add_u64 v[84:85], s[28:29], 2, v[84:85]
	s_lshl_b32 s50, s57, 2
	v_lshl_add_u64 v[84:85], v[84:85], 0, s[50:51]
	v_add_f32_e32 v82, v82, v83
	global_store_dword v[84:85], v82, off offset:16 sc1

.LBB0_1239:
	v_lshlrev_b64 v[82:83], 12, v[188:189]
	v_lshlrev_b32_e32 v84, 16, v134
	v_and_b32_e32 v85, 0xffff0000, v134
	v_lshlrev_b32_e32 v86, 16, v135
	v_and_b32_e32 v87, 0xffff0000, v135
	v_lshlrev_b32_e32 v88, 16, v136
	v_and_b32_e32 v89, 0xffff0000, v136
	v_lshlrev_b32_e32 v90, 16, v137
	v_and_b32_e32 v91, 0xffff0000, v137
	v_lshl_add_u64 v[82:83], s[12:13], 0, v[82:83]
	v_pk_fma_f32 v[80:81], v[80:81], 0.5, v[86:87] op_sel_hi:[1,0,1]
	v_pk_fma_f32 v[78:79], v[78:79], 0.5, v[84:85] op_sel_hi:[1,0,1]
	v_pk_fma_f32 v[76:77], v[76:77], 0.5, v[90:91] op_sel_hi:[1,0,1]
	v_pk_fma_f32 v[74:75], v[74:75], 0.5, v[88:89] op_sel_hi:[1,0,1]
	s_and_b64 vcc, exec, s[8:9]
	v_lshl_add_u64 v[86:87], v[180:181], 2, v[82:83]
	s_cbranch_vccnz .LBB0_1241
	s_mov_b64 s[30:31], 0
	global_store_dwordx4 v[86:87], v[78:81], off sc1
	global_store_dwordx4 v[86:87], v[74:77], off offset:16 sc1
	s_branch .LBB0_1242

.LBB0_1242:
	v_lshl_add_u64 v[84:85], s[16:17], 0, v[186:187]
	v_lshlrev_b64 v[82:83], 7, v[188:189]
	s_andn2_b64 vcc, exec, s[30:31]
	v_lshl_add_u64 v[84:85], v[180:181], 1, v[84:85]
	s_cbranch_vccnz .LBB0_1246
	v_cvt_pk_bf16_f32 v88, v78, v79
	v_mul_f32_e32 v79, v79, v79
	v_fmac_f32_e32 v79, v78, v78
	v_mul_f32_e32 v78, v81, v81
	v_fmac_f32_e32 v78, v80, v80
	v_add_f32_e32 v78, v79, v78
	v_mul_f32_e32 v79, v75, v75
	v_fmac_f32_e32 v79, v74, v74
	v_add_f32_e32 v78, v79, v78
	v_mul_f32_e32 v79, v77, v77
	v_fmac_f32_e32 v79, v76, v76
	v_add_f32_e32 v78, v79, v78
	ds_swizzle_b32 v79, v78 offset:swizzle(SWAP,16)
	v_cvt_pk_bf16_f32 v90, v74, v75
	v_cvt_pk_bf16_f32 v89, v80, v81
	v_cvt_pk_bf16_f32 v91, v76, v77
	global_store_dwordx4 v[84:85], v[88:91], off sc1
	s_waitcnt lgkmcnt(0)
	v_add_f32_e32 v74, v78, v79
	v_mov_b32_e32 v75, v74
	s_nop 1
	v_permlane32_swap_b32_e32 v74, v75
	s_and_saveexec_b64 s[30:31], s[4:5]
	s_cbranch_execz .LBB0_1245
	v_lshl_add_u64 v[76:77], s[18:19], 0, v[82:83]
	v_lshl_add_u64 v[76:77], s[28:29], 2, v[76:77]
	s_lshl_b32 s50, s57, 2
	v_lshl_add_u64 v[76:77], v[76:77], 0, s[50:51]
	v_add_f32_e32 v74, v74, v75
	global_store_dword v[76:77], v74, off sc1

.LBB0_1246:
	v_lshlrev_b32_e32 v74, 16, v130
	v_and_b32_e32 v75, 0xffff0000, v130
	v_lshlrev_b32_e32 v76, 16, v131
	v_and_b32_e32 v77, 0xffff0000, v131
	v_lshlrev_b32_e32 v78, 16, v132
	v_and_b32_e32 v79, 0xffff0000, v132
	v_lshlrev_b32_e32 v80, 16, v133
	v_and_b32_e32 v81, 0xffff0000, v133
	v_pk_fma_f32 v[72:73], v[72:73], 0.5, v[76:77] op_sel_hi:[1,0,1]
	v_pk_fma_f32 v[70:71], v[70:71], 0.5, v[74:75] op_sel_hi:[1,0,1]
	v_pk_fma_f32 v[68:69], v[68:69], 0.5, v[80:81] op_sel_hi:[1,0,1]
	s_and_b64 vcc, exec, s[8:9]
	v_pk_fma_f32 v[66:67], v[66:67], 0.5, v[78:79] op_sel_hi:[1,0,1]
	s_cbranch_vccnz .LBB0_1248
	global_store_dwordx4 v[86:87], v[70:73], off offset:512 sc1
	global_store_dwordx4 v[86:87], v[66:69], off offset:528 sc1
	s_cbranch_execz .LBB0_1249
	s_branch .LBB0_1252
.LBB0_1248:
.LBB0_1249:
	v_cvt_pk_bf16_f32 v74, v70, v71
	v_mul_f32_e32 v71, v71, v71
	v_fmac_f32_e32 v71, v70, v70
	v_mul_f32_e32 v70, v73, v73
	v_fmac_f32_e32 v70, v72, v72
	v_add_f32_e32 v70, v71, v70
	v_mul_f32_e32 v71, v67, v67
	v_fmac_f32_e32 v71, v66, v66
	v_add_f32_e32 v70, v71, v70
	v_mul_f32_e32 v71, v69, v69
	v_fmac_f32_e32 v71, v68, v68
	v_add_f32_e32 v70, v71, v70
	ds_swizzle_b32 v71, v70 offset:swizzle(SWAP,16)
	v_cvt_pk_bf16_f32 v76, v66, v67
	v_cvt_pk_bf16_f32 v75, v72, v73
	v_cvt_pk_bf16_f32 v77, v68, v69
	global_store_dwordx4 v[84:85], v[74:77], off offset:256 sc1
	s_waitcnt lgkmcnt(0)
	v_add_f32_e32 v66, v70, v71
	v_mov_b32_e32 v67, v66
	s_nop 1
	v_permlane32_swap_b32_e32 v66, v67
	s_and_saveexec_b64 s[30:31], s[4:5]
	s_cbranch_execz .LBB0_1251
	v_lshl_add_u64 v[68:69], s[18:19], 0, v[82:83]
	v_lshl_add_u64 v[68:69], s[28:29], 2, v[68:69]
	s_lshl_b32 s50, s57, 2
	v_lshl_add_u64 v[68:69], v[68:69], 0, s[50:51]
	v_add_f32_e32 v66, v66, v67
	global_store_dword v[68:69], v66, off offset:16 sc1

.LBB0_1252:
	v_lshl_add_u64 v[106:107], v[182:183], 0, s[54:55]
	v_lshlrev_b64 v[108:109], 11, v[106:107]
	v_lshl_add_u64 v[104:105], v[182:183], 0, s[0:1]
	v_lshl_add_u64 v[66:67], v[184:185], 0, v[108:109]
	v_lshlrev_b64 v[102:103], 11, v[104:105]
	v_lshl_add_u64 v[100:101], v[182:183], 0, s[66:67]
	global_load_dwordx4 v[110:113], v[66:67], off
	global_load_dwordx4 v[90:93], v[66:67], off offset:256
	v_lshl_add_u64 v[66:67], v[184:185], 0, v[102:103]
	v_lshlrev_b64 v[98:99], 11, v[100:101]
	v_lshl_add_u64 v[96:97], v[182:183], 0, s[68:69]
	global_load_dwordx4 v[86:89], v[66:67], off
	global_load_dwordx4 v[82:85], v[66:67], off offset:256
	v_lshl_add_u64 v[66:67], v[184:185], 0, v[98:99]
	v_lshlrev_b64 v[94:95], 11, v[96:97]
	global_load_dwordx4 v[78:81], v[66:67], off
	global_load_dwordx4 v[74:77], v[66:67], off offset:256
	v_lshl_add_u64 v[66:67], v[184:185], 0, v[94:95]
	global_load_dwordx4 v[70:73], v[66:67], off
	s_nop 0
	global_load_dwordx4 v[66:69], v[66:67], off offset:256
	v_lshlrev_b64 v[114:115], 12, v[106:107]
	v_lshl_add_u64 v[114:115], s[12:13], 0, v[114:115]
	s_and_b64 vcc, exec, s[8:9]
	s_waitcnt vmcnt(7)
	v_lshlrev_b32_e32 v116, 16, v110
	v_and_b32_e32 v117, 0xffff0000, v110
	v_lshlrev_b32_e32 v110, 16, v111
	v_and_b32_e32 v111, 0xffff0000, v111
	v_lshlrev_b32_e32 v118, 16, v112
	v_and_b32_e32 v119, 0xffff0000, v112
	v_lshlrev_b32_e32 v112, 16, v113
	v_and_b32_e32 v113, 0xffff0000, v113
	v_pk_fma_f32 v[64:65], v[64:65], 0.5, v[110:111] op_sel_hi:[1,0,1]
	v_pk_fma_f32 v[62:63], v[62:63], 0.5, v[116:117] op_sel_hi:[1,0,1]
	v_pk_fma_f32 v[60:61], v[60:61], 0.5, v[112:113] op_sel_hi:[1,0,1]
	v_pk_fma_f32 v[58:59], v[58:59], 0.5, v[118:119] op_sel_hi:[1,0,1]
	v_lshl_add_u64 v[110:111], v[180:181], 2, v[114:115]
	s_cbranch_vccnz .LBB0_1254
	s_mov_b64 s[30:31], 0
	global_store_dwordx4 v[110:111], v[62:65], off sc1
	global_store_dwordx4 v[110:111], v[58:61], off offset:16 sc1
	s_branch .LBB0_1255

.LBB0_1255:
	v_lshl_add_u64 v[108:109], s[16:17], 0, v[108:109]
	v_lshlrev_b64 v[106:107], 7, v[106:107]
	s_andn2_b64 vcc, exec, s[30:31]
	v_lshl_add_u64 v[108:109], v[180:181], 1, v[108:109]
	s_cbranch_vccnz .LBB0_1259
	v_cvt_pk_bf16_f32 v112, v62, v63
	v_mul_f32_e32 v63, v63, v63
	v_fmac_f32_e32 v63, v62, v62
	v_mul_f32_e32 v62, v65, v65
	v_fmac_f32_e32 v62, v64, v64
	v_add_f32_e32 v62, v63, v62
	v_mul_f32_e32 v63, v59, v59
	v_fmac_f32_e32 v63, v58, v58
	v_add_f32_e32 v62, v63, v62
	v_mul_f32_e32 v63, v61, v61
	v_fmac_f32_e32 v63, v60, v60
	v_add_f32_e32 v62, v63, v62
	ds_swizzle_b32 v63, v62 offset:swizzle(SWAP,16)
	v_cvt_pk_bf16_f32 v114, v58, v59
	v_cvt_pk_bf16_f32 v113, v64, v65
	v_cvt_pk_bf16_f32 v115, v60, v61
	global_store_dwordx4 v[108:109], v[112:115], off sc1
	s_waitcnt lgkmcnt(0)
	v_add_f32_e32 v58, v62, v63
	v_mov_b32_e32 v59, v58
	s_nop 1
	v_permlane32_swap_b32_e32 v58, v59
	s_and_saveexec_b64 s[30:31], s[4:5]
	s_cbranch_execz .LBB0_1258
	v_lshl_add_u64 v[60:61], s[18:19], 0, v[106:107]
	v_lshl_add_u64 v[60:61], s[28:29], 2, v[60:61]
	s_lshl_b32 s50, s57, 2
	v_lshl_add_u64 v[60:61], v[60:61], 0, s[50:51]
	v_add_f32_e32 v58, v58, v59
	global_store_dword v[60:61], v58, off sc1

.LBB0_1259:
	s_waitcnt vmcnt(6)
	v_lshlrev_b32_e32 v58, 16, v90
	v_and_b32_e32 v59, 0xffff0000, v90
	v_lshlrev_b32_e32 v60, 16, v91
	v_and_b32_e32 v61, 0xffff0000, v91
	v_lshlrev_b32_e32 v62, 16, v92
	v_and_b32_e32 v63, 0xffff0000, v92
	v_lshlrev_b32_e32 v64, 16, v93
	v_and_b32_e32 v65, 0xffff0000, v93
	v_pk_fma_f32 v[56:57], v[56:57], 0.5, v[60:61] op_sel_hi:[1,0,1]
	v_pk_fma_f32 v[54:55], v[54:55], 0.5, v[58:59] op_sel_hi:[1,0,1]
	v_pk_fma_f32 v[52:53], v[52:53], 0.5, v[64:65] op_sel_hi:[1,0,1]
	s_and_b64 vcc, exec, s[8:9]
	v_pk_fma_f32 v[50:51], v[50:51], 0.5, v[62:63] op_sel_hi:[1,0,1]
	s_cbranch_vccnz .LBB0_1261
	global_store_dwordx4 v[110:111], v[54:57], off offset:512 sc1
	global_store_dwordx4 v[110:111], v[50:53], off offset:528 sc1
	s_cbranch_execz .LBB0_1262
	s_branch .LBB0_1265
.LBB0_1261:
.LBB0_1262:
	v_cvt_pk_bf16_f32 v58, v54, v55
	v_mul_f32_e32 v55, v55, v55
	v_fmac_f32_e32 v55, v54, v54
	v_mul_f32_e32 v54, v57, v57
	v_fmac_f32_e32 v54, v56, v56
	v_add_f32_e32 v54, v55, v54
	v_mul_f32_e32 v55, v51, v51
	v_fmac_f32_e32 v55, v50, v50
	v_add_f32_e32 v54, v55, v54
	v_mul_f32_e32 v55, v53, v53
	v_fmac_f32_e32 v55, v52, v52
	v_add_f32_e32 v54, v55, v54
	ds_swizzle_b32 v55, v54 offset:swizzle(SWAP,16)
	v_cvt_pk_bf16_f32 v60, v50, v51
	v_cvt_pk_bf16_f32 v59, v56, v57
	v_cvt_pk_bf16_f32 v61, v52, v53
	global_store_dwordx4 v[108:109], v[58:61], off offset:256 sc1
	s_waitcnt lgkmcnt(0)
	v_add_f32_e32 v50, v54, v55
	v_mov_b32_e32 v51, v50
	s_nop 1
	v_permlane32_swap_b32_e32 v50, v51
	s_and_saveexec_b64 s[30:31], s[4:5]
	s_cbranch_execz .LBB0_1264
	v_lshl_add_u64 v[52:53], s[18:19], 0, v[106:107]
	v_lshl_add_u64 v[52:53], s[28:29], 2, v[52:53]
	s_lshl_b32 s50, s57, 2
	v_lshl_add_u64 v[52:53], v[52:53], 0, s[50:51]
	v_add_f32_e32 v50, v50, v51
	global_store_dword v[52:53], v50, off offset:16 sc1

.LBB0_1265:
	v_lshlrev_b64 v[50:51], 12, v[104:105]
	s_waitcnt vmcnt(5)
	v_lshlrev_b32_e32 v52, 16, v86
	v_and_b32_e32 v53, 0xffff0000, v86
	v_lshlrev_b32_e32 v54, 16, v87
	v_and_b32_e32 v55, 0xffff0000, v87
	v_lshlrev_b32_e32 v56, 16, v88
	v_and_b32_e32 v57, 0xffff0000, v88
	v_lshlrev_b32_e32 v58, 16, v89
	v_and_b32_e32 v59, 0xffff0000, v89
	v_lshl_add_u64 v[50:51], s[12:13], 0, v[50:51]
	v_pk_fma_f32 v[48:49], v[48:49], 0.5, v[54:55] op_sel_hi:[1,0,1]
	v_pk_fma_f32 v[46:47], v[46:47], 0.5, v[52:53] op_sel_hi:[1,0,1]
	v_pk_fma_f32 v[44:45], v[44:45], 0.5, v[58:59] op_sel_hi:[1,0,1]
	v_pk_fma_f32 v[42:43], v[42:43], 0.5, v[56:57] op_sel_hi:[1,0,1]
	s_and_b64 vcc, exec, s[8:9]
	v_lshl_add_u64 v[54:55], v[180:181], 2, v[50:51]
	s_cbranch_vccnz .LBB0_1267
	s_mov_b64 s[30:31], 0
	global_store_dwordx4 v[54:55], v[46:49], off sc1
	global_store_dwordx4 v[54:55], v[42:45], off offset:16 sc1
	s_branch .LBB0_1268

.LBB0_1268:
	v_lshl_add_u64 v[52:53], s[16:17], 0, v[102:103]
	v_lshlrev_b64 v[50:51], 7, v[104:105]
	s_andn2_b64 vcc, exec, s[30:31]
	v_lshl_add_u64 v[52:53], v[180:181], 1, v[52:53]
	s_cbranch_vccnz .LBB0_1272
	v_cvt_pk_bf16_f32 v56, v46, v47
	v_mul_f32_e32 v47, v47, v47
	v_fmac_f32_e32 v47, v46, v46
	v_mul_f32_e32 v46, v49, v49
	v_fmac_f32_e32 v46, v48, v48
	v_add_f32_e32 v46, v47, v46
	v_mul_f32_e32 v47, v43, v43
	v_fmac_f32_e32 v47, v42, v42
	v_add_f32_e32 v46, v47, v46
	v_mul_f32_e32 v47, v45, v45
	v_fmac_f32_e32 v47, v44, v44
	v_add_f32_e32 v46, v47, v46
	ds_swizzle_b32 v47, v46 offset:swizzle(SWAP,16)
	v_cvt_pk_bf16_f32 v58, v42, v43
	v_cvt_pk_bf16_f32 v57, v48, v49
	v_cvt_pk_bf16_f32 v59, v44, v45
	global_store_dwordx4 v[52:53], v[56:59], off sc1
	s_waitcnt lgkmcnt(0)
	v_add_f32_e32 v42, v46, v47
	v_mov_b32_e32 v43, v42
	s_nop 1
	v_permlane32_swap_b32_e32 v42, v43
	s_and_saveexec_b64 s[30:31], s[4:5]
	s_cbranch_execz .LBB0_1271
	v_lshl_add_u64 v[44:45], s[18:19], 0, v[50:51]
	v_lshl_add_u64 v[44:45], s[28:29], 2, v[44:45]
	s_lshl_b32 s50, s57, 2
	v_lshl_add_u64 v[44:45], v[44:45], 0, s[50:51]
	v_add_f32_e32 v42, v42, v43
	global_store_dword v[44:45], v42, off sc1

.LBB0_1272:
	s_waitcnt vmcnt(4)
	v_lshlrev_b32_e32 v42, 16, v82
	v_and_b32_e32 v43, 0xffff0000, v82
	v_lshlrev_b32_e32 v44, 16, v83
	v_and_b32_e32 v45, 0xffff0000, v83
	v_lshlrev_b32_e32 v46, 16, v84
	v_and_b32_e32 v47, 0xffff0000, v84
	v_lshlrev_b32_e32 v48, 16, v85
	v_and_b32_e32 v49, 0xffff0000, v85
	v_pk_fma_f32 v[40:41], v[40:41], 0.5, v[44:45] op_sel_hi:[1,0,1]
	v_pk_fma_f32 v[38:39], v[38:39], 0.5, v[42:43] op_sel_hi:[1,0,1]
	v_pk_fma_f32 v[36:37], v[36:37], 0.5, v[48:49] op_sel_hi:[1,0,1]
	s_and_b64 vcc, exec, s[8:9]
	v_pk_fma_f32 v[34:35], v[34:35], 0.5, v[46:47] op_sel_hi:[1,0,1]
	s_cbranch_vccnz .LBB0_1274
	global_store_dwordx4 v[54:55], v[38:41], off offset:512 sc1
	global_store_dwordx4 v[54:55], v[34:37], off offset:528 sc1
	s_cbranch_execz .LBB0_1275
	s_branch .LBB0_1278
.LBB0_1274:
.LBB0_1275:
	v_cvt_pk_bf16_f32 v42, v38, v39
	v_mul_f32_e32 v39, v39, v39
	v_fmac_f32_e32 v39, v38, v38
	v_mul_f32_e32 v38, v41, v41
	v_fmac_f32_e32 v38, v40, v40
	v_add_f32_e32 v38, v39, v38
	v_mul_f32_e32 v39, v35, v35
	v_fmac_f32_e32 v39, v34, v34
	v_add_f32_e32 v38, v39, v38
	v_mul_f32_e32 v39, v37, v37
	v_fmac_f32_e32 v39, v36, v36
	v_add_f32_e32 v38, v39, v38
	ds_swizzle_b32 v39, v38 offset:swizzle(SWAP,16)
	v_cvt_pk_bf16_f32 v44, v34, v35
	v_cvt_pk_bf16_f32 v43, v40, v41
	v_cvt_pk_bf16_f32 v45, v36, v37
	global_store_dwordx4 v[52:53], v[42:45], off offset:256 sc1
	s_waitcnt lgkmcnt(0)
	v_add_f32_e32 v34, v38, v39
	v_mov_b32_e32 v35, v34
	s_nop 1
	v_permlane32_swap_b32_e32 v34, v35
	s_and_saveexec_b64 s[30:31], s[4:5]
	s_cbranch_execz .LBB0_1277
	v_lshl_add_u64 v[36:37], s[18:19], 0, v[50:51]
	v_lshl_add_u64 v[36:37], s[28:29], 2, v[36:37]
	s_lshl_b32 s50, s57, 2
	v_lshl_add_u64 v[36:37], v[36:37], 0, s[50:51]
	v_add_f32_e32 v34, v34, v35
	global_store_dword v[36:37], v34, off offset:16 sc1

.LBB0_1278:
	v_lshlrev_b64 v[34:35], 12, v[100:101]
	s_waitcnt vmcnt(3)
	v_lshlrev_b32_e32 v36, 16, v78
	v_and_b32_e32 v37, 0xffff0000, v78
	v_lshlrev_b32_e32 v38, 16, v79
	v_and_b32_e32 v39, 0xffff0000, v79
	v_lshlrev_b32_e32 v40, 16, v80
	v_and_b32_e32 v41, 0xffff0000, v80
	v_lshlrev_b32_e32 v42, 16, v81
	v_and_b32_e32 v43, 0xffff0000, v81
	v_lshl_add_u64 v[34:35], s[12:13], 0, v[34:35]
	v_pk_fma_f32 v[32:33], v[32:33], 0.5, v[38:39] op_sel_hi:[1,0,1]
	v_pk_fma_f32 v[30:31], v[30:31], 0.5, v[36:37] op_sel_hi:[1,0,1]
	v_pk_fma_f32 v[28:29], v[28:29], 0.5, v[42:43] op_sel_hi:[1,0,1]
	v_pk_fma_f32 v[26:27], v[26:27], 0.5, v[40:41] op_sel_hi:[1,0,1]
	s_and_b64 vcc, exec, s[8:9]
	v_lshl_add_u64 v[38:39], v[180:181], 2, v[34:35]
	s_cbranch_vccnz .LBB0_1280
	s_mov_b64 s[30:31], 0
	global_store_dwordx4 v[38:39], v[30:33], off sc1
	global_store_dwordx4 v[38:39], v[26:29], off offset:16 sc1
	s_branch .LBB0_1281

.LBB0_1281:
	v_lshl_add_u64 v[36:37], s[16:17], 0, v[98:99]
	v_lshlrev_b64 v[34:35], 7, v[100:101]
	s_andn2_b64 vcc, exec, s[30:31]
	v_lshl_add_u64 v[36:37], v[180:181], 1, v[36:37]
	s_cbranch_vccnz .LBB0_1285
	v_cvt_pk_bf16_f32 v40, v30, v31
	v_mul_f32_e32 v31, v31, v31
	v_fmac_f32_e32 v31, v30, v30
	v_mul_f32_e32 v30, v33, v33
	v_fmac_f32_e32 v30, v32, v32
	v_add_f32_e32 v30, v31, v30
	v_mul_f32_e32 v31, v27, v27
	v_fmac_f32_e32 v31, v26, v26
	v_add_f32_e32 v30, v31, v30
	v_mul_f32_e32 v31, v29, v29
	v_fmac_f32_e32 v31, v28, v28
	v_add_f32_e32 v30, v31, v30
	ds_swizzle_b32 v31, v30 offset:swizzle(SWAP,16)
	v_cvt_pk_bf16_f32 v42, v26, v27
	v_cvt_pk_bf16_f32 v41, v32, v33
	v_cvt_pk_bf16_f32 v43, v28, v29
	global_store_dwordx4 v[36:37], v[40:43], off sc1
	s_waitcnt lgkmcnt(0)
	v_add_f32_e32 v26, v30, v31
	v_mov_b32_e32 v27, v26
	s_nop 1
	v_permlane32_swap_b32_e32 v26, v27
	s_and_saveexec_b64 s[30:31], s[4:5]
	s_cbranch_execz .LBB0_1284
	v_lshl_add_u64 v[28:29], s[18:19], 0, v[34:35]
	v_lshl_add_u64 v[28:29], s[28:29], 2, v[28:29]
	s_lshl_b32 s50, s57, 2
	v_lshl_add_u64 v[28:29], v[28:29], 0, s[50:51]
	v_add_f32_e32 v26, v26, v27
	global_store_dword v[28:29], v26, off sc1

.LBB0_1285:
	s_waitcnt vmcnt(2)
	v_lshlrev_b32_e32 v26, 16, v74
	v_and_b32_e32 v27, 0xffff0000, v74
	v_lshlrev_b32_e32 v28, 16, v75
	v_and_b32_e32 v29, 0xffff0000, v75
	v_lshlrev_b32_e32 v30, 16, v76
	v_and_b32_e32 v31, 0xffff0000, v76
	v_lshlrev_b32_e32 v32, 16, v77
	v_and_b32_e32 v33, 0xffff0000, v77
	v_pk_fma_f32 v[24:25], v[24:25], 0.5, v[28:29] op_sel_hi:[1,0,1]
	v_pk_fma_f32 v[22:23], v[22:23], 0.5, v[26:27] op_sel_hi:[1,0,1]
	v_pk_fma_f32 v[20:21], v[20:21], 0.5, v[32:33] op_sel_hi:[1,0,1]
	s_and_b64 vcc, exec, s[8:9]
	v_pk_fma_f32 v[18:19], v[18:19], 0.5, v[30:31] op_sel_hi:[1,0,1]
	s_cbranch_vccnz .LBB0_1287
	global_store_dwordx4 v[38:39], v[22:25], off offset:512 sc1
	global_store_dwordx4 v[38:39], v[18:21], off offset:528 sc1
	s_cbranch_execz .LBB0_1288
	s_branch .LBB0_1291
.LBB0_1287:
.LBB0_1288:
	v_cvt_pk_bf16_f32 v26, v22, v23
	v_mul_f32_e32 v23, v23, v23
	v_fmac_f32_e32 v23, v22, v22
	v_mul_f32_e32 v22, v25, v25
	v_fmac_f32_e32 v22, v24, v24
	v_add_f32_e32 v22, v23, v22
	v_mul_f32_e32 v23, v19, v19
	v_fmac_f32_e32 v23, v18, v18
	v_add_f32_e32 v22, v23, v22
	v_mul_f32_e32 v23, v21, v21
	v_fmac_f32_e32 v23, v20, v20
	v_add_f32_e32 v22, v23, v22
	ds_swizzle_b32 v23, v22 offset:swizzle(SWAP,16)
	v_cvt_pk_bf16_f32 v28, v18, v19
	v_cvt_pk_bf16_f32 v27, v24, v25
	v_cvt_pk_bf16_f32 v29, v20, v21
	global_store_dwordx4 v[36:37], v[26:29], off offset:256 sc1
	s_waitcnt lgkmcnt(0)
	v_add_f32_e32 v18, v22, v23
	v_mov_b32_e32 v19, v18
	s_nop 1
	v_permlane32_swap_b32_e32 v18, v19
	s_and_saveexec_b64 s[30:31], s[4:5]
	s_cbranch_execz .LBB0_1290
	v_lshl_add_u64 v[20:21], s[18:19], 0, v[34:35]
	v_lshl_add_u64 v[20:21], s[28:29], 2, v[20:21]
	s_lshl_b32 s50, s57, 2
	v_lshl_add_u64 v[20:21], v[20:21], 0, s[50:51]
	v_add_f32_e32 v18, v18, v19
	global_store_dword v[20:21], v18, off offset:16 sc1

.LBB0_1291:
	v_lshlrev_b64 v[18:19], 12, v[96:97]
	s_waitcnt vmcnt(1)
	v_lshlrev_b32_e32 v20, 16, v70
	v_and_b32_e32 v21, 0xffff0000, v70
	v_lshlrev_b32_e32 v22, 16, v71
	v_and_b32_e32 v23, 0xffff0000, v71
	v_lshlrev_b32_e32 v24, 16, v72
	v_and_b32_e32 v25, 0xffff0000, v72
	v_lshlrev_b32_e32 v26, 16, v73
	v_and_b32_e32 v27, 0xffff0000, v73
	v_lshl_add_u64 v[18:19], s[12:13], 0, v[18:19]
	v_pk_fma_f32 v[16:17], v[16:17], 0.5, v[22:23] op_sel_hi:[1,0,1]
	v_pk_fma_f32 v[14:15], v[14:15], 0.5, v[20:21] op_sel_hi:[1,0,1]
	v_pk_fma_f32 v[12:13], v[12:13], 0.5, v[26:27] op_sel_hi:[1,0,1]
	v_pk_fma_f32 v[10:11], v[10:11], 0.5, v[24:25] op_sel_hi:[1,0,1]
	s_and_b64 vcc, exec, s[8:9]
	v_lshl_add_u64 v[22:23], v[180:181], 2, v[18:19]
	s_cbranch_vccnz .LBB0_1293
	s_mov_b64 s[30:31], 0
	global_store_dwordx4 v[22:23], v[14:17], off sc1
	global_store_dwordx4 v[22:23], v[10:13], off offset:16 sc1
	s_branch .LBB0_1294

.LBB0_1294:
	v_lshl_add_u64 v[20:21], s[16:17], 0, v[94:95]
	v_lshlrev_b64 v[18:19], 7, v[96:97]
	s_andn2_b64 vcc, exec, s[30:31]
	v_lshl_add_u64 v[20:21], v[180:181], 1, v[20:21]
	s_cbranch_vccnz .LBB0_1298
	v_cvt_pk_bf16_f32 v24, v14, v15
	v_mul_f32_e32 v15, v15, v15
	v_fmac_f32_e32 v15, v14, v14
	v_mul_f32_e32 v14, v17, v17
	v_fmac_f32_e32 v14, v16, v16
	v_add_f32_e32 v14, v15, v14
	v_mul_f32_e32 v15, v11, v11
	v_fmac_f32_e32 v15, v10, v10
	v_add_f32_e32 v14, v15, v14
	v_mul_f32_e32 v15, v13, v13
	v_fmac_f32_e32 v15, v12, v12
	v_add_f32_e32 v14, v15, v14
	ds_swizzle_b32 v15, v14 offset:swizzle(SWAP,16)
	v_cvt_pk_bf16_f32 v26, v10, v11
	v_cvt_pk_bf16_f32 v25, v16, v17
	v_cvt_pk_bf16_f32 v27, v12, v13
	global_store_dwordx4 v[20:21], v[24:27], off sc1
	s_waitcnt lgkmcnt(0)
	v_add_f32_e32 v10, v14, v15
	v_mov_b32_e32 v11, v10
	s_nop 1
	v_permlane32_swap_b32_e32 v10, v11
	s_and_saveexec_b64 s[30:31], s[4:5]
	s_cbranch_execz .LBB0_1297
	v_lshl_add_u64 v[12:13], s[18:19], 0, v[18:19]
	v_lshl_add_u64 v[12:13], s[28:29], 2, v[12:13]
	s_lshl_b32 s50, s57, 2
	v_lshl_add_u64 v[12:13], v[12:13], 0, s[50:51]
	v_add_f32_e32 v10, v10, v11
	global_store_dword v[12:13], v10, off sc1

.LBB0_1298:
	s_waitcnt vmcnt(0)
	v_lshlrev_b32_e32 v10, 16, v66
	v_and_b32_e32 v11, 0xffff0000, v66
	v_lshlrev_b32_e32 v12, 16, v67
	v_and_b32_e32 v13, 0xffff0000, v67
	v_lshlrev_b32_e32 v14, 16, v68
	v_and_b32_e32 v15, 0xffff0000, v68
	v_lshlrev_b32_e32 v16, 16, v69
	v_and_b32_e32 v17, 0xffff0000, v69
	v_pk_fma_f32 v[8:9], v[8:9], 0.5, v[12:13] op_sel_hi:[1,0,1]
	v_pk_fma_f32 v[6:7], v[6:7], 0.5, v[10:11] op_sel_hi:[1,0,1]
	v_pk_fma_f32 v[4:5], v[4:5], 0.5, v[16:17] op_sel_hi:[1,0,1]
	s_and_b64 vcc, exec, s[8:9]
	v_pk_fma_f32 v[2:3], v[2:3], 0.5, v[14:15] op_sel_hi:[1,0,1]
	s_cbranch_vccnz .LBB0_1303
	global_store_dwordx4 v[22:23], v[6:9], off offset:512 sc1
	global_store_dwordx4 v[22:23], v[2:5], off offset:528 sc1
	s_cbranch_execnz .LBB0_1304
.LBB0_1300:
	v_cvt_pk_bf16_f32 v10, v6, v7
	v_mul_f32_e32 v7, v7, v7
	v_fmac_f32_e32 v7, v6, v6
	v_mul_f32_e32 v6, v9, v9
	v_fmac_f32_e32 v6, v8, v8
	v_add_f32_e32 v6, v7, v6
	v_mul_f32_e32 v7, v3, v3
	v_fmac_f32_e32 v7, v2, v2
	v_add_f32_e32 v6, v7, v6
	v_mul_f32_e32 v7, v5, v5
	v_fmac_f32_e32 v7, v4, v4
	v_add_f32_e32 v6, v7, v6
	ds_swizzle_b32 v7, v6 offset:swizzle(SWAP,16)
	v_cvt_pk_bf16_f32 v12, v2, v3
	v_cvt_pk_bf16_f32 v11, v8, v9
	v_cvt_pk_bf16_f32 v13, v4, v5
	global_store_dwordx4 v[20:21], v[10:13], off offset:256 sc1
	s_waitcnt lgkmcnt(0)
	v_add_f32_e32 v2, v6, v7
	v_mov_b32_e32 v3, v2
	s_nop 1
	v_permlane32_swap_b32_e32 v2, v3
	s_and_saveexec_b64 s[8:9], s[4:5]
	s_cbranch_execz .LBB0_1302
	v_lshl_add_u64 v[4:5], s[18:19], 0, v[18:19]
	v_lshl_add_u64 v[4:5], s[28:29], 2, v[4:5]
	s_lshl_b32 s50, s57, 2
	v_lshl_add_u64 v[4:5], v[4:5], 0, s[50:51]
	v_add_f32_e32 v2, v2, v3
	global_store_dword v[4:5], v2, off offset:16 sc1
